# attention: static s_setprio 1 given to the older (non-lag) half instead of the lag half
# baseline (speedup 1.0000x reference)
.LBB0_356:
	s_or_b64 exec, exec, s[0:1]
	s_sub_i32 s0, 4, s15
	v_cvt_f32_u32_e32 v16, s0
	s_add_i32 s0, 0, 0x21040
	s_waitcnt lgkmcnt(0)
	s_barrier
	v_mul_f32_e32 v16, -2.0, v16
	v_exp_f32_e32 v16, v16
	s_nop 0
	v_mul_f32_e32 v157, 0x3fb8aa3b, v16
	v_mov_b32_e32 v16, s0
	ds_read_b128 v[16:19], v16
	v_readlane_b32 s0, v253, 45
	s_waitcnt lgkmcnt(0)
	v_max_f32_e32 v16, v16, v16
	v_max_f32_e32 v16, 0, v16
	v_max3_f32 v16, v16, v17, v18
	v_mov_b32_e32 v17, s0
	ds_read_b128 v[20:23], v17
	s_waitcnt lgkmcnt(0)
	v_max3_f32 v16, v16, v19, v20
	v_max3_f32 v16, v16, v21, v22
	v_max3_f32 v16, v16, v23, 0
	v_add_f32_e32 v16, 0x42480000, v16
	v_div_scale_f32 v17, s[0:1], v157, v157, v16
	v_rcp_f32_e32 v18, v17
	s_nop 0
	v_fma_f32 v19, -v17, v18, 1.0
	v_fmac_f32_e32 v18, v19, v18
	v_div_scale_f32 v19, vcc, v16, v157, v16
	v_mul_f32_e32 v20, v19, v18
	v_fma_f32 v21, -v17, v20, v19
	v_fmac_f32_e32 v20, v21, v18
	v_fma_f32 v17, -v17, v20, v19
	v_div_fmas_f32 v17, v17, v18, v20
	v_div_fixup_f32 v16, v17, v157, v16
	v_min_f32_e32 v16, 0x46000000, v16
	v_cvt_i32_f32_e32 v16, v16
	v_sub_u32_e32 v17, s14, v16
	v_subrev_u32_e32 v18, s14, v16
	v_add_u32_e32 v16, s14, v16
	v_add_u32_e32 v16, 0x7f, v16
	v_ashrrev_i32_e32 v16, 6, v16
	v_ashrrev_i32_e32 v17, 6, v17
	v_cmp_gt_i32_e32 vcc, 1, v18
	v_min_i32_e32 v16, 63, v16
	s_nop 0
	v_cndmask_b32_e32 v17, 0, v17, vcc
	v_readfirstlane_b32 s0, v16
	v_cndmask_b32_e64 v16, 0, 1, s[54:55]
	v_readfirstlane_b32 s14, v17
	v_cmp_ne_u32_e64 s[10:11], 1, v16
	s_andn2_b64 vcc, exec, s[54:55]
	s_cbranch_vccz .LBB0_358
	s_setprio 1
